# GEMM K-loops: LDS-DMA addresses in SADDR form (scalar base + 32-bit VGPR offset, k-step as immediate with M0 compensated) - 64 64-bit VALU adds removed from the four loops
# baseline (speedup 1.0000x reference)
.LBB0_135:
	s_add_u32 s6, s52, 0xfffc0080
	s_addc_u32 s7, s53, -1
	s_add_i32 s24, 0, 0x10000
	s_cmp_eq_u32 s72, 12
	s_cselect_b32 s57, s47, s7
	s_cselect_b32 s56, s68, s6
	v_add_u32_e32 v148, s24, v151
	s_cselect_b32 s55, s45, s71
	s_cselect_b32 s54, s69, s70
	s_add_i32 s25, 0, 0x14000
	ds_read_b128 v[140:143], v148
	ds_read_b128 v[144:147], v148 offset:1024
	ds_read_b128 v[156:159], v148 offset:2048
	ds_read_b128 v[160:163], v148 offset:3072
	v_add_u32_e32 v148, s25, v151
	ds_read_b128 v[164:167], v148
	ds_read_b128 v[168:171], v148 offset:1024
	ds_read_b128 v[172:175], v148 offset:2048
	ds_read_b128 v[176:179], v148 offset:3072
	s_add_i32 m0, s61, 0xc000
	ds_read_b128 v[180:183], v154
	ds_read_b128 v[184:187], v154 offset:1024
	ds_read_b128 v[188:191], v154 offset:2048
	ds_read_b128 v[192:195], v154 offset:3072
	ds_read_b128 v[196:199], v154 offset:4096
	ds_read_b128 v[200:203], v154 offset:5120
	ds_read_b128 v[204:207], v154 offset:6144
	ds_read_b128 v[208:211], v154 offset:7168
	global_load_lds_dwordx4 v136, s[52:53]
	s_add_i32 m0, s61, 0xe000
	s_nop 0
	global_load_lds_dwordx4 v138, s[52:53]
	s_waitcnt vmcnt(8)
	s_waitcnt lgkmcnt(0)
	s_barrier
	s_setprio 1
	v_mfma_f32_16x16x32_bf16 v[126:129], v[140:143], v[180:183], v[126:129]
	v_mfma_f32_16x16x32_bf16 v[122:125], v[156:159], v[180:183], v[122:125]
	v_mfma_f32_16x16x32_bf16 v[110:113], v[140:143], v[188:191], v[110:113]
	v_mfma_f32_16x16x32_bf16 v[106:109], v[156:159], v[188:191], v[106:109]
	v_mfma_f32_16x16x32_bf16 v[94:97], v[140:143], v[196:199], v[94:97]
	v_mfma_f32_16x16x32_bf16 v[90:93], v[156:159], v[196:199], v[90:93]
	v_mfma_f32_16x16x32_bf16 v[78:81], v[140:143], v[204:207], v[78:81]
	v_mfma_f32_16x16x32_bf16 v[74:77], v[156:159], v[204:207], v[74:77]
	v_mfma_f32_16x16x32_bf16 v[126:129], v[144:147], v[184:187], v[126:129]
	v_mfma_f32_16x16x32_bf16 v[122:125], v[160:163], v[184:187], v[122:125]
	v_mfma_f32_16x16x32_bf16 v[110:113], v[144:147], v[192:195], v[110:113]
	v_mfma_f32_16x16x32_bf16 v[106:109], v[160:163], v[192:195], v[106:109]
	v_mfma_f32_16x16x32_bf16 v[94:97], v[144:147], v[200:203], v[94:97]
	v_mfma_f32_16x16x32_bf16 v[90:93], v[160:163], v[200:203], v[90:93]
	v_mfma_f32_16x16x32_bf16 v[78:81], v[144:147], v[208:211], v[78:81]
	v_mfma_f32_16x16x32_bf16 v[74:77], v[160:163], v[208:211], v[74:77]
	v_mfma_f32_16x16x32_bf16 v[118:121], v[164:167], v[180:183], v[118:121]
	v_mfma_f32_16x16x32_bf16 v[114:117], v[172:175], v[180:183], v[114:117]
	v_mfma_f32_16x16x32_bf16 v[102:105], v[164:167], v[188:191], v[102:105]
	v_mfma_f32_16x16x32_bf16 v[98:101], v[172:175], v[188:191], v[98:101]
	v_mfma_f32_16x16x32_bf16 v[86:89], v[164:167], v[196:199], v[86:89]
	v_mfma_f32_16x16x32_bf16 v[82:85], v[172:175], v[196:199], v[82:85]
	v_mfma_f32_16x16x32_bf16 v[70:73], v[164:167], v[204:207], v[70:73]
	v_mfma_f32_16x16x32_bf16 v[66:69], v[172:175], v[204:207], v[66:69]
	v_mfma_f32_16x16x32_bf16 v[118:121], v[168:171], v[184:187], v[118:121]
	v_mfma_f32_16x16x32_bf16 v[114:117], v[176:179], v[184:187], v[114:117]
	v_mfma_f32_16x16x32_bf16 v[102:105], v[168:171], v[192:195], v[102:105]
	v_mfma_f32_16x16x32_bf16 v[98:101], v[176:179], v[192:195], v[98:101]
	v_mfma_f32_16x16x32_bf16 v[86:89], v[168:171], v[200:203], v[86:89]
	v_mfma_f32_16x16x32_bf16 v[82:85], v[176:179], v[200:203], v[82:85]
	v_mfma_f32_16x16x32_bf16 v[70:73], v[168:171], v[208:211], v[70:73]
	v_mfma_f32_16x16x32_bf16 v[66:69], v[176:179], v[208:211], v[66:69]
	s_setprio 0
	s_barrier
	s_add_i32 s6, s24, s60
	s_mov_b32 m0, s6
	ds_read_b128 v[180:183], v154 offset:16384
	ds_read_b128 v[184:187], v154 offset:17408
	ds_read_b128 v[188:191], v154 offset:18432
	ds_read_b128 v[192:195], v154 offset:19456
	ds_read_b128 v[196:199], v154 offset:20480
	ds_read_b128 v[200:203], v154 offset:21504
	ds_read_b128 v[204:207], v154 offset:22528
	ds_read_b128 v[208:211], v154 offset:23552
	global_load_lds_dwordx4 v0, s[54:55]
	s_add_i32 m0, s6, 0x2000
	s_add_u32 s6, s54, 0x40000
	s_addc_u32 s7, s55, 0
	s_add_i32 s24, s25, s60
	global_load_lds_dwordx4 v130, s[54:55]
	s_mov_b32 m0, s24
	s_nop 0
	global_load_lds_dwordx4 v0, s[6:7]
	s_add_i32 m0, s24, 0x2000
	s_nop 0
	global_load_lds_dwordx4 v130, s[6:7]
	s_mov_b32 m0, s61
	s_nop 0
	global_load_lds_dwordx4 v134, s[56:57]
	s_mov_b32 m0, s62
	s_nop 0
	global_load_lds_dwordx4 v132, s[56:57]
	s_waitcnt vmcnt(8)
	s_waitcnt lgkmcnt(0)
	s_barrier
	s_setprio 1
	v_mfma_f32_16x16x32_bf16 v[62:65], v[140:143], v[180:183], v[62:65]
	v_mfma_f32_16x16x32_bf16 v[58:61], v[156:159], v[180:183], v[58:61]
	v_mfma_f32_16x16x32_bf16 v[46:49], v[140:143], v[188:191], v[46:49]
	v_mfma_f32_16x16x32_bf16 v[42:45], v[156:159], v[188:191], v[42:45]
	v_mfma_f32_16x16x32_bf16 v[30:33], v[140:143], v[196:199], v[30:33]
	v_mfma_f32_16x16x32_bf16 v[26:29], v[156:159], v[196:199], v[26:29]
	v_mfma_f32_16x16x32_bf16 v[14:17], v[140:143], v[204:207], v[14:17]
	v_mfma_f32_16x16x32_bf16 v[10:13], v[156:159], v[204:207], v[10:13]
	v_mfma_f32_16x16x32_bf16 v[62:65], v[144:147], v[184:187], v[62:65]
	v_mfma_f32_16x16x32_bf16 v[58:61], v[160:163], v[184:187], v[58:61]
	v_mfma_f32_16x16x32_bf16 v[46:49], v[144:147], v[192:195], v[46:49]
	v_mfma_f32_16x16x32_bf16 v[42:45], v[160:163], v[192:195], v[42:45]
	v_mfma_f32_16x16x32_bf16 v[30:33], v[144:147], v[200:203], v[30:33]
	v_mfma_f32_16x16x32_bf16 v[26:29], v[160:163], v[200:203], v[26:29]
	v_mfma_f32_16x16x32_bf16 v[14:17], v[144:147], v[208:211], v[14:17]
	v_mfma_f32_16x16x32_bf16 v[10:13], v[160:163], v[208:211], v[10:13]
	v_mfma_f32_16x16x32_bf16 v[54:57], v[164:167], v[180:183], v[54:57]
	v_mfma_f32_16x16x32_bf16 v[50:53], v[172:175], v[180:183], v[50:53]
	v_mfma_f32_16x16x32_bf16 v[38:41], v[164:167], v[188:191], v[38:41]
	v_mfma_f32_16x16x32_bf16 v[34:37], v[172:175], v[188:191], v[34:37]
	v_mfma_f32_16x16x32_bf16 v[22:25], v[164:167], v[196:199], v[22:25]
	v_mfma_f32_16x16x32_bf16 v[18:21], v[172:175], v[196:199], v[18:21]
	v_mfma_f32_16x16x32_bf16 v[6:9], v[164:167], v[204:207], v[6:9]
	v_mfma_f32_16x16x32_bf16 v[2:5], v[172:175], v[204:207], v[2:5]
	v_mfma_f32_16x16x32_bf16 v[54:57], v[168:171], v[184:187], v[54:57]
	v_mfma_f32_16x16x32_bf16 v[50:53], v[176:179], v[184:187], v[50:53]
	v_mfma_f32_16x16x32_bf16 v[38:41], v[168:171], v[192:195], v[38:41]
	v_mfma_f32_16x16x32_bf16 v[34:37], v[176:179], v[192:195], v[34:37]
	v_mfma_f32_16x16x32_bf16 v[22:25], v[168:171], v[200:203], v[22:25]
	v_mfma_f32_16x16x32_bf16 v[18:21], v[176:179], v[200:203], v[18:21]
	v_mfma_f32_16x16x32_bf16 v[6:9], v[168:171], v[208:211], v[6:9]
	v_mfma_f32_16x16x32_bf16 v[2:5], v[176:179], v[208:211], v[2:5]
	s_setprio 0
	s_barrier
	s_add_i32 s24, 0, 0x18000
	v_add_u32_e32 v155, s24, v151
	s_add_i32 s25, 0, 0x1c000
	ds_read_b128 v[140:143], v155
	ds_read_b128 v[144:147], v155 offset:1024
	ds_read_b128 v[156:159], v155 offset:2048
	ds_read_b128 v[160:163], v155 offset:3072
	v_add_u32_e32 v155, s25, v151
	ds_read_b128 v[164:167], v155
	ds_read_b128 v[168:171], v155 offset:1024
	ds_read_b128 v[172:175], v155 offset:2048
	ds_read_b128 v[176:179], v155 offset:3072
	s_add_u32 s6, s56, 0x40000
	s_addc_u32 s7, s57, 0
	s_mov_b32 m0, s63
	ds_read_b128 v[180:183], v154 offset:32768
	ds_read_b128 v[184:187], v154 offset:33792
	ds_read_b128 v[188:191], v154 offset:34816
	ds_read_b128 v[192:195], v154 offset:35840
	ds_read_b128 v[196:199], v154 offset:36864
	ds_read_b128 v[200:203], v154 offset:37888
	ds_read_b128 v[204:207], v154 offset:38912
	ds_read_b128 v[208:211], v154 offset:39936
	global_load_lds_dwordx4 v134, s[6:7]
	s_mov_b32 m0, s64
	s_nop 0
	global_load_lds_dwordx4 v132, s[6:7]
	s_waitcnt vmcnt(8)
	s_waitcnt lgkmcnt(0)
	s_barrier
	s_setprio 1
	v_mfma_f32_16x16x32_bf16 v[126:129], v[140:143], v[180:183], v[126:129]
	v_mfma_f32_16x16x32_bf16 v[122:125], v[156:159], v[180:183], v[122:125]
	v_mfma_f32_16x16x32_bf16 v[110:113], v[140:143], v[188:191], v[110:113]
	v_mfma_f32_16x16x32_bf16 v[106:109], v[156:159], v[188:191], v[106:109]
	v_mfma_f32_16x16x32_bf16 v[94:97], v[140:143], v[196:199], v[94:97]
	v_mfma_f32_16x16x32_bf16 v[90:93], v[156:159], v[196:199], v[90:93]
	v_mfma_f32_16x16x32_bf16 v[78:81], v[140:143], v[204:207], v[78:81]
	v_mfma_f32_16x16x32_bf16 v[74:77], v[156:159], v[204:207], v[74:77]
	v_mfma_f32_16x16x32_bf16 v[126:129], v[144:147], v[184:187], v[126:129]
	v_mfma_f32_16x16x32_bf16 v[122:125], v[160:163], v[184:187], v[122:125]
	v_mfma_f32_16x16x32_bf16 v[110:113], v[144:147], v[192:195], v[110:113]
	v_mfma_f32_16x16x32_bf16 v[106:109], v[160:163], v[192:195], v[106:109]
	v_mfma_f32_16x16x32_bf16 v[94:97], v[144:147], v[200:203], v[94:97]
	v_mfma_f32_16x16x32_bf16 v[90:93], v[160:163], v[200:203], v[90:93]
	v_mfma_f32_16x16x32_bf16 v[78:81], v[144:147], v[208:211], v[78:81]
	v_mfma_f32_16x16x32_bf16 v[74:77], v[160:163], v[208:211], v[74:77]
	v_mfma_f32_16x16x32_bf16 v[118:121], v[164:167], v[180:183], v[118:121]
	v_mfma_f32_16x16x32_bf16 v[114:117], v[172:175], v[180:183], v[114:117]
	v_mfma_f32_16x16x32_bf16 v[102:105], v[164:167], v[188:191], v[102:105]
	v_mfma_f32_16x16x32_bf16 v[98:101], v[172:175], v[188:191], v[98:101]
	v_mfma_f32_16x16x32_bf16 v[86:89], v[164:167], v[196:199], v[86:89]
	v_mfma_f32_16x16x32_bf16 v[82:85], v[172:175], v[196:199], v[82:85]
	v_mfma_f32_16x16x32_bf16 v[70:73], v[164:167], v[204:207], v[70:73]
	v_mfma_f32_16x16x32_bf16 v[66:69], v[172:175], v[204:207], v[66:69]
	v_mfma_f32_16x16x32_bf16 v[118:121], v[168:171], v[184:187], v[118:121]
	v_mfma_f32_16x16x32_bf16 v[114:117], v[176:179], v[184:187], v[114:117]
	v_mfma_f32_16x16x32_bf16 v[102:105], v[168:171], v[192:195], v[102:105]
	v_mfma_f32_16x16x32_bf16 v[98:101], v[176:179], v[192:195], v[98:101]
	v_mfma_f32_16x16x32_bf16 v[86:89], v[168:171], v[200:203], v[86:89]
	v_mfma_f32_16x16x32_bf16 v[82:85], v[176:179], v[200:203], v[82:85]
	v_mfma_f32_16x16x32_bf16 v[70:73], v[168:171], v[208:211], v[70:73]
	v_mfma_f32_16x16x32_bf16 v[66:69], v[176:179], v[208:211], v[66:69]
	s_setprio 0
	s_barrier
	s_add_i32 s6, s24, s60
	s_add_i32 m0, s6, 0xffffff80
	ds_read_b128 v[180:183], v154 offset:49152
	ds_read_b128 v[184:187], v154 offset:50176
	ds_read_b128 v[188:191], v154 offset:51200
	ds_read_b128 v[192:195], v154 offset:52224
	ds_read_b128 v[196:199], v154 offset:53248
	ds_read_b128 v[200:203], v154 offset:54272
	ds_read_b128 v[204:207], v154 offset:55296
	ds_read_b128 v[208:211], v154 offset:56320
	global_load_lds_dwordx4 v0, s[54:55] offset:128
	s_add_i32 m0, s6, 0x1f80
	s_add_u32 s6, s54, 0x40080
	s_addc_u32 s7, s55, 0
	s_add_i32 s24, s25, s60
	global_load_lds_dwordx4 v130, s[54:55] offset:128
	s_mov_b32 m0, s24
	s_nop 0
	global_load_lds_dwordx4 v0, s[6:7]
	s_add_i32 m0, s24, 0x2000
	s_nop 0
	global_load_lds_dwordx4 v130, s[6:7]
	s_add_i32 m0, s65, 0xffffff80
	s_nop 0
	global_load_lds_dwordx4 v134, s[56:57] offset:128
	s_add_i32 m0, s66, 0xffffff80
	s_nop 0
	global_load_lds_dwordx4 v132, s[56:57] offset:128
	s_waitcnt vmcnt(8)
	s_waitcnt lgkmcnt(0)
	s_barrier
	s_setprio 1
	v_mfma_f32_16x16x32_bf16 v[62:65], v[140:143], v[180:183], v[62:65]
	v_mfma_f32_16x16x32_bf16 v[58:61], v[156:159], v[180:183], v[58:61]
	v_mfma_f32_16x16x32_bf16 v[46:49], v[140:143], v[188:191], v[46:49]
	v_mfma_f32_16x16x32_bf16 v[42:45], v[156:159], v[188:191], v[42:45]
	v_mfma_f32_16x16x32_bf16 v[30:33], v[140:143], v[196:199], v[30:33]
	v_mfma_f32_16x16x32_bf16 v[26:29], v[156:159], v[196:199], v[26:29]
	v_mfma_f32_16x16x32_bf16 v[14:17], v[140:143], v[204:207], v[14:17]
	v_mfma_f32_16x16x32_bf16 v[10:13], v[156:159], v[204:207], v[10:13]
	v_mfma_f32_16x16x32_bf16 v[62:65], v[144:147], v[184:187], v[62:65]
	v_mfma_f32_16x16x32_bf16 v[58:61], v[160:163], v[184:187], v[58:61]
	v_mfma_f32_16x16x32_bf16 v[46:49], v[144:147], v[192:195], v[46:49]
	v_mfma_f32_16x16x32_bf16 v[42:45], v[160:163], v[192:195], v[42:45]
	v_mfma_f32_16x16x32_bf16 v[30:33], v[144:147], v[200:203], v[30:33]
	v_mfma_f32_16x16x32_bf16 v[26:29], v[160:163], v[200:203], v[26:29]
	v_mfma_f32_16x16x32_bf16 v[14:17], v[144:147], v[208:211], v[14:17]
	v_mfma_f32_16x16x32_bf16 v[10:13], v[160:163], v[208:211], v[10:13]
	v_mfma_f32_16x16x32_bf16 v[54:57], v[164:167], v[180:183], v[54:57]
	v_mfma_f32_16x16x32_bf16 v[50:53], v[172:175], v[180:183], v[50:53]
	v_mfma_f32_16x16x32_bf16 v[38:41], v[164:167], v[188:191], v[38:41]
	v_mfma_f32_16x16x32_bf16 v[34:37], v[172:175], v[188:191], v[34:37]
	v_mfma_f32_16x16x32_bf16 v[22:25], v[164:167], v[196:199], v[22:25]
	v_mfma_f32_16x16x32_bf16 v[18:21], v[172:175], v[196:199], v[18:21]
	v_mfma_f32_16x16x32_bf16 v[6:9], v[164:167], v[204:207], v[6:9]
	v_mfma_f32_16x16x32_bf16 v[2:5], v[172:175], v[204:207], v[2:5]
	v_mfma_f32_16x16x32_bf16 v[54:57], v[168:171], v[184:187], v[54:57]
	v_mfma_f32_16x16x32_bf16 v[50:53], v[176:179], v[184:187], v[50:53]
	v_mfma_f32_16x16x32_bf16 v[38:41], v[168:171], v[192:195], v[38:41]
	v_mfma_f32_16x16x32_bf16 v[34:37], v[176:179], v[192:195], v[34:37]
	v_mfma_f32_16x16x32_bf16 v[22:25], v[168:171], v[200:203], v[22:25]
	v_mfma_f32_16x16x32_bf16 v[18:21], v[176:179], v[200:203], v[18:21]
	v_mfma_f32_16x16x32_bf16 v[6:9], v[168:171], v[208:211], v[6:9]
	v_mfma_f32_16x16x32_bf16 v[2:5], v[176:179], v[208:211], v[2:5]
	s_setprio 0
	s_barrier
	s_add_i32 s72, s72, 2
	s_add_u32 s52, s52, 0x100
	s_addc_u32 s53, s53, 0
	s_add_u32 s70, s70, 0x100
	s_addc_u32 s71, s71, 0
	s_cmp_gt_u32 s72, 13
	s_cbranch_scc0 .LBB0_135
	s_and_b64 vcc, exec, s[42:43]
	s_cbranch_vccz .LBB0_138
	s_barrier

.LBB0_231:
	s_add_u32 s6, s0, 0xfffc0080
	s_addc_u32 s7, s1, -1
	s_add_i32 s24, 0, 0x10000
	s_cmp_eq_u32 s71, 12
	s_cselect_b32 s43, s37, s7
	s_cselect_b32 s42, s53, s6
	v_add_u32_e32 v0, s24, v177
	s_cselect_b32 s41, s51, s70
	s_cselect_b32 s40, s58, s59
	s_add_i32 s6, 0, 0x14000
	ds_read_b128 v[10:13], v0
	ds_read_b128 v[14:17], v0 offset:1024
	ds_read_b128 v[26:29], v0 offset:2048
	ds_read_b128 v[30:33], v0 offset:3072
	v_add_u32_e32 v0, s6, v177
	ds_read_b128 v[146:149], v0
	ds_read_b128 v[150:153], v0 offset:1024
	ds_read_b128 v[166:169], v0 offset:2048
	ds_read_b128 v[170:173], v0 offset:3072
	s_add_i32 m0, s63, 0xc000
	ds_read_b128 v[182:185], v180
	ds_read_b128 v[186:189], v180 offset:1024
	ds_read_b128 v[190:193], v180 offset:2048
	ds_read_b128 v[194:197], v180 offset:3072
	ds_read_b128 v[198:201], v180 offset:4096
	ds_read_b128 v[202:205], v180 offset:5120
	ds_read_b128 v[206:209], v180 offset:6144
	ds_read_b128 v[210:213], v180 offset:7168
	global_load_lds_dwordx4 v162, s[0:1]
	s_add_i32 m0, s63, 0xe000
	s_nop 0
	global_load_lds_dwordx4 v164, s[0:1]
	s_waitcnt vmcnt(8)
	s_waitcnt lgkmcnt(0)
	s_barrier
	s_setprio 1
	v_mfma_f32_16x16x32_bf16 v[142:145], v[10:13], v[182:185], v[142:145]
	v_mfma_f32_16x16x32_bf16 v[138:141], v[26:29], v[182:185], v[138:141]
	v_mfma_f32_16x16x32_bf16 v[126:129], v[10:13], v[190:193], v[126:129]
	v_mfma_f32_16x16x32_bf16 v[122:125], v[26:29], v[190:193], v[122:125]
	v_mfma_f32_16x16x32_bf16 v[110:113], v[10:13], v[198:201], v[110:113]
	v_mfma_f32_16x16x32_bf16 v[106:109], v[26:29], v[198:201], v[106:109]
	v_mfma_f32_16x16x32_bf16 v[94:97], v[10:13], v[206:209], v[94:97]
	v_mfma_f32_16x16x32_bf16 v[90:93], v[26:29], v[206:209], v[90:93]
	v_mfma_f32_16x16x32_bf16 v[142:145], v[14:17], v[186:189], v[142:145]
	v_mfma_f32_16x16x32_bf16 v[138:141], v[30:33], v[186:189], v[138:141]
	v_mfma_f32_16x16x32_bf16 v[126:129], v[14:17], v[194:197], v[126:129]
	v_mfma_f32_16x16x32_bf16 v[122:125], v[30:33], v[194:197], v[122:125]
	v_mfma_f32_16x16x32_bf16 v[110:113], v[14:17], v[202:205], v[110:113]
	v_mfma_f32_16x16x32_bf16 v[106:109], v[30:33], v[202:205], v[106:109]
	v_mfma_f32_16x16x32_bf16 v[94:97], v[14:17], v[210:213], v[94:97]
	v_mfma_f32_16x16x32_bf16 v[90:93], v[30:33], v[210:213], v[90:93]
	v_mfma_f32_16x16x32_bf16 v[134:137], v[146:149], v[182:185], v[134:137]
	v_mfma_f32_16x16x32_bf16 v[130:133], v[166:169], v[182:185], v[130:133]
	v_mfma_f32_16x16x32_bf16 v[118:121], v[146:149], v[190:193], v[118:121]
	v_mfma_f32_16x16x32_bf16 v[114:117], v[166:169], v[190:193], v[114:117]
	v_mfma_f32_16x16x32_bf16 v[102:105], v[146:149], v[198:201], v[102:105]
	v_mfma_f32_16x16x32_bf16 v[98:101], v[166:169], v[198:201], v[98:101]
	v_mfma_f32_16x16x32_bf16 v[86:89], v[146:149], v[206:209], v[86:89]
	v_mfma_f32_16x16x32_bf16 v[82:85], v[166:169], v[206:209], v[82:85]
	v_mfma_f32_16x16x32_bf16 v[134:137], v[150:153], v[186:189], v[134:137]
	v_mfma_f32_16x16x32_bf16 v[130:133], v[170:173], v[186:189], v[130:133]
	v_mfma_f32_16x16x32_bf16 v[118:121], v[150:153], v[194:197], v[118:121]
	v_mfma_f32_16x16x32_bf16 v[114:117], v[170:173], v[194:197], v[114:117]
	v_mfma_f32_16x16x32_bf16 v[102:105], v[150:153], v[202:205], v[102:105]
	v_mfma_f32_16x16x32_bf16 v[98:101], v[170:173], v[202:205], v[98:101]
	v_mfma_f32_16x16x32_bf16 v[86:89], v[150:153], v[210:213], v[86:89]
	v_mfma_f32_16x16x32_bf16 v[82:85], v[170:173], v[210:213], v[82:85]
	s_setprio 0
	s_barrier
	s_add_i32 s7, s24, s62
	s_mov_b32 m0, s7
	ds_read_b128 v[182:185], v180 offset:16384
	ds_read_b128 v[186:189], v180 offset:17408
	ds_read_b128 v[190:193], v180 offset:18432
	ds_read_b128 v[194:197], v180 offset:19456
	ds_read_b128 v[198:201], v180 offset:20480
	ds_read_b128 v[202:205], v180 offset:21504
	ds_read_b128 v[206:209], v180 offset:22528
	ds_read_b128 v[210:213], v180 offset:23552
	global_load_lds_dwordx4 v158, s[40:41]
	s_add_i32 m0, s7, 0x2000
	s_add_u32 s24, s40, 0x40000
	s_addc_u32 s25, s41, 0
	s_add_i32 s6, s6, s62
	global_load_lds_dwordx4 v154, s[40:41]
	s_mov_b32 m0, s6
	s_nop 0
	global_load_lds_dwordx4 v158, s[24:25]
	s_add_i32 m0, s6, 0x2000
	s_nop 0
	global_load_lds_dwordx4 v154, s[24:25]
	s_mov_b32 m0, s63
	s_nop 0
	global_load_lds_dwordx4 v160, s[42:43]
	s_mov_b32 m0, s64
	s_nop 0
	global_load_lds_dwordx4 v156, s[42:43]
	s_waitcnt vmcnt(8)
	s_waitcnt lgkmcnt(0)
	s_barrier
	s_setprio 1
	v_mfma_f32_16x16x32_bf16 v[78:81], v[10:13], v[182:185], v[78:81]
	v_mfma_f32_16x16x32_bf16 v[74:77], v[26:29], v[182:185], v[74:77]
	v_mfma_f32_16x16x32_bf16 v[62:65], v[10:13], v[190:193], v[62:65]
	v_mfma_f32_16x16x32_bf16 v[58:61], v[26:29], v[190:193], v[58:61]
	v_mfma_f32_16x16x32_bf16 v[46:49], v[10:13], v[198:201], v[46:49]
	v_mfma_f32_16x16x32_bf16 v[42:45], v[26:29], v[198:201], v[42:45]
	v_mfma_f32_16x16x32_bf16 v[10:13], v[10:13], v[206:209], v[22:25]
	v_mfma_f32_16x16x32_bf16 v[78:81], v[14:17], v[186:189], v[78:81]
	v_mfma_f32_16x16x32_bf16 v[74:77], v[30:33], v[186:189], v[74:77]
	v_mfma_f32_16x16x32_bf16 v[62:65], v[14:17], v[194:197], v[62:65]
	v_mfma_f32_16x16x32_bf16 v[58:61], v[30:33], v[194:197], v[58:61]
	v_mfma_f32_16x16x32_bf16 v[46:49], v[14:17], v[202:205], v[46:49]
	v_mfma_f32_16x16x32_bf16 v[42:45], v[30:33], v[202:205], v[42:45]
	v_mfma_f32_16x16x32_bf16 v[10:13], v[14:17], v[210:213], v[10:13]
	v_mfma_f32_16x16x32_bf16 v[14:17], v[26:29], v[206:209], v[18:21]
	v_mfma_f32_16x16x32_bf16 v[14:17], v[30:33], v[210:213], v[14:17]
	v_mfma_f32_16x16x32_bf16 v[18:21], v[146:149], v[182:185], v[70:73]
	v_mfma_f32_16x16x32_bf16 v[26:29], v[150:153], v[186:189], v[18:21]
	v_mfma_f32_16x16x32_bf16 v[18:21], v[166:169], v[182:185], v[66:69]
	v_mfma_f32_16x16x32_bf16 v[30:33], v[170:173], v[186:189], v[18:21]
	v_mfma_f32_16x16x32_bf16 v[18:21], v[146:149], v[190:193], v[54:57]
	v_mfma_f32_16x16x32_bf16 v[54:57], v[150:153], v[194:197], v[18:21]
	v_mfma_f32_16x16x32_bf16 v[18:21], v[166:169], v[190:193], v[50:53]
	v_mfma_f32_16x16x32_bf16 v[50:53], v[170:173], v[194:197], v[18:21]
	v_mfma_f32_16x16x32_bf16 v[18:21], v[146:149], v[198:201], v[38:41]
	v_mfma_f32_16x16x32_bf16 v[38:41], v[150:153], v[202:205], v[18:21]
	v_mfma_f32_16x16x32_bf16 v[18:21], v[166:169], v[198:201], v[34:37]
	v_mfma_f32_16x16x32_bf16 v[6:9], v[146:149], v[206:209], v[6:9]
	v_mfma_f32_16x16x32_bf16 v[2:5], v[166:169], v[206:209], v[2:5]
	v_mfma_f32_16x16x32_bf16 v[34:37], v[170:173], v[202:205], v[18:21]
	v_mfma_f32_16x16x32_bf16 v[6:9], v[150:153], v[210:213], v[6:9]
	v_mfma_f32_16x16x32_bf16 v[2:5], v[170:173], v[210:213], v[2:5]
	s_setprio 0
	s_barrier
	s_add_i32 s6, 0, 0x18000
	v_add_u32_e32 v0, s6, v177
	s_add_i32 s7, 0, 0x1c000
	ds_read_b128 v[18:21], v0
	ds_read_b128 v[22:25], v0 offset:1024
	ds_read_b128 v[66:69], v0 offset:2048
	ds_read_b128 v[70:73], v0 offset:3072
	v_add_u32_e32 v0, s7, v177
	ds_read_b128 v[146:149], v0
	ds_read_b128 v[150:153], v0 offset:1024
	ds_read_b128 v[166:169], v0 offset:2048
	ds_read_b128 v[170:173], v0 offset:3072
	s_add_u32 s24, s42, 0x40000
	s_addc_u32 s25, s43, 0
	s_mov_b32 m0, s65
	ds_read_b128 v[182:185], v180 offset:32768
	ds_read_b128 v[186:189], v180 offset:33792
	ds_read_b128 v[190:193], v180 offset:34816
	ds_read_b128 v[194:197], v180 offset:35840
	ds_read_b128 v[198:201], v180 offset:36864
	ds_read_b128 v[202:205], v180 offset:37888
	ds_read_b128 v[206:209], v180 offset:38912
	ds_read_b128 v[210:213], v180 offset:39936
	global_load_lds_dwordx4 v160, s[24:25]
	s_mov_b32 m0, s66
	s_nop 0
	global_load_lds_dwordx4 v156, s[24:25]
	s_waitcnt vmcnt(8)
	s_waitcnt lgkmcnt(0)
	s_barrier
	s_setprio 1
	v_mfma_f32_16x16x32_bf16 v[142:145], v[18:21], v[182:185], v[142:145]
	v_mfma_f32_16x16x32_bf16 v[138:141], v[66:69], v[182:185], v[138:141]
	v_mfma_f32_16x16x32_bf16 v[126:129], v[18:21], v[190:193], v[126:129]
	v_mfma_f32_16x16x32_bf16 v[122:125], v[66:69], v[190:193], v[122:125]
	v_mfma_f32_16x16x32_bf16 v[110:113], v[18:21], v[198:201], v[110:113]
	v_mfma_f32_16x16x32_bf16 v[106:109], v[66:69], v[198:201], v[106:109]
	v_mfma_f32_16x16x32_bf16 v[94:97], v[18:21], v[206:209], v[94:97]
	v_mfma_f32_16x16x32_bf16 v[90:93], v[66:69], v[206:209], v[90:93]
	v_mfma_f32_16x16x32_bf16 v[142:145], v[22:25], v[186:189], v[142:145]
	v_mfma_f32_16x16x32_bf16 v[138:141], v[70:73], v[186:189], v[138:141]
	v_mfma_f32_16x16x32_bf16 v[126:129], v[22:25], v[194:197], v[126:129]
	v_mfma_f32_16x16x32_bf16 v[122:125], v[70:73], v[194:197], v[122:125]
	v_mfma_f32_16x16x32_bf16 v[110:113], v[22:25], v[202:205], v[110:113]
	v_mfma_f32_16x16x32_bf16 v[106:109], v[70:73], v[202:205], v[106:109]
	v_mfma_f32_16x16x32_bf16 v[94:97], v[22:25], v[210:213], v[94:97]
	v_mfma_f32_16x16x32_bf16 v[90:93], v[70:73], v[210:213], v[90:93]
	v_mfma_f32_16x16x32_bf16 v[134:137], v[146:149], v[182:185], v[134:137]
	v_mfma_f32_16x16x32_bf16 v[130:133], v[166:169], v[182:185], v[130:133]
	v_mfma_f32_16x16x32_bf16 v[118:121], v[146:149], v[190:193], v[118:121]
	v_mfma_f32_16x16x32_bf16 v[114:117], v[166:169], v[190:193], v[114:117]
	v_mfma_f32_16x16x32_bf16 v[102:105], v[146:149], v[198:201], v[102:105]
	v_mfma_f32_16x16x32_bf16 v[98:101], v[166:169], v[198:201], v[98:101]
	v_mfma_f32_16x16x32_bf16 v[86:89], v[146:149], v[206:209], v[86:89]
	v_mfma_f32_16x16x32_bf16 v[82:85], v[166:169], v[206:209], v[82:85]
	v_mfma_f32_16x16x32_bf16 v[134:137], v[150:153], v[186:189], v[134:137]
	v_mfma_f32_16x16x32_bf16 v[130:133], v[170:173], v[186:189], v[130:133]
	v_mfma_f32_16x16x32_bf16 v[118:121], v[150:153], v[194:197], v[118:121]
	v_mfma_f32_16x16x32_bf16 v[114:117], v[170:173], v[194:197], v[114:117]
	v_mfma_f32_16x16x32_bf16 v[102:105], v[150:153], v[202:205], v[102:105]
	v_mfma_f32_16x16x32_bf16 v[98:101], v[170:173], v[202:205], v[98:101]
	v_mfma_f32_16x16x32_bf16 v[86:89], v[150:153], v[210:213], v[86:89]
	v_mfma_f32_16x16x32_bf16 v[82:85], v[170:173], v[210:213], v[82:85]
	s_setprio 0
	s_barrier
	s_add_i32 s6, s6, s62
	s_add_i32 m0, s6, 0xffffff80
	ds_read_b128 v[182:185], v180 offset:49152
	ds_read_b128 v[186:189], v180 offset:50176
	ds_read_b128 v[190:193], v180 offset:51200
	ds_read_b128 v[194:197], v180 offset:52224
	ds_read_b128 v[198:201], v180 offset:53248
	ds_read_b128 v[202:205], v180 offset:54272
	ds_read_b128 v[206:209], v180 offset:55296
	ds_read_b128 v[210:213], v180 offset:56320
	global_load_lds_dwordx4 v158, s[40:41] offset:128
	s_add_i32 m0, s6, 0x1f80
	s_add_u32 s24, s40, 0x40080
	s_addc_u32 s25, s41, 0
	s_add_i32 s6, s7, s62
	global_load_lds_dwordx4 v154, s[40:41] offset:128
	s_mov_b32 m0, s6
	s_nop 0
	global_load_lds_dwordx4 v158, s[24:25]
	s_add_i32 m0, s6, 0x2000
	s_nop 0
	global_load_lds_dwordx4 v154, s[24:25]
	s_add_i32 m0, s8, 0xffffff80
	s_nop 0
	global_load_lds_dwordx4 v160, s[42:43] offset:128
	s_add_i32 m0, s67, 0xffffff80
	s_nop 0
	global_load_lds_dwordx4 v156, s[42:43] offset:128
	s_waitcnt vmcnt(8)
	s_waitcnt lgkmcnt(0)
	s_barrier
	s_setprio 1
	v_mfma_f32_16x16x32_bf16 v[78:81], v[18:21], v[182:185], v[78:81]
	v_mfma_f32_16x16x32_bf16 v[62:65], v[18:21], v[190:193], v[62:65]
	v_mfma_f32_16x16x32_bf16 v[46:49], v[18:21], v[198:201], v[46:49]
	v_mfma_f32_16x16x32_bf16 v[10:13], v[18:21], v[206:209], v[10:13]
	v_mfma_f32_16x16x32_bf16 v[78:81], v[22:25], v[186:189], v[78:81]
	v_mfma_f32_16x16x32_bf16 v[74:77], v[66:69], v[182:185], v[74:77]
	v_mfma_f32_16x16x32_bf16 v[62:65], v[22:25], v[194:197], v[62:65]
	v_mfma_f32_16x16x32_bf16 v[58:61], v[66:69], v[190:193], v[58:61]
	v_mfma_f32_16x16x32_bf16 v[46:49], v[22:25], v[202:205], v[46:49]
	v_mfma_f32_16x16x32_bf16 v[42:45], v[66:69], v[198:201], v[42:45]
	v_mfma_f32_16x16x32_bf16 v[22:25], v[22:25], v[210:213], v[10:13]
	v_mfma_f32_16x16x32_bf16 v[10:13], v[66:69], v[206:209], v[14:17]
	v_mfma_f32_16x16x32_bf16 v[74:77], v[70:73], v[186:189], v[74:77]
	v_mfma_f32_16x16x32_bf16 v[58:61], v[70:73], v[194:197], v[58:61]
	v_mfma_f32_16x16x32_bf16 v[42:45], v[70:73], v[202:205], v[42:45]
	v_mfma_f32_16x16x32_bf16 v[18:21], v[70:73], v[210:213], v[10:13]
	v_mfma_f32_16x16x32_bf16 v[10:13], v[146:149], v[182:185], v[26:29]
	v_mfma_f32_16x16x32_bf16 v[70:73], v[150:153], v[186:189], v[10:13]
	v_mfma_f32_16x16x32_bf16 v[10:13], v[166:169], v[182:185], v[30:33]
	v_mfma_f32_16x16x32_bf16 v[66:69], v[170:173], v[186:189], v[10:13]
	v_mfma_f32_16x16x32_bf16 v[10:13], v[146:149], v[190:193], v[54:57]
	v_mfma_f32_16x16x32_bf16 v[54:57], v[150:153], v[194:197], v[10:13]
	v_mfma_f32_16x16x32_bf16 v[10:13], v[166:169], v[190:193], v[50:53]
	v_mfma_f32_16x16x32_bf16 v[50:53], v[170:173], v[194:197], v[10:13]
	v_mfma_f32_16x16x32_bf16 v[10:13], v[146:149], v[198:201], v[38:41]
	v_mfma_f32_16x16x32_bf16 v[38:41], v[150:153], v[202:205], v[10:13]
	v_mfma_f32_16x16x32_bf16 v[10:13], v[166:169], v[198:201], v[34:37]
	v_mfma_f32_16x16x32_bf16 v[6:9], v[146:149], v[206:209], v[6:9]
	v_mfma_f32_16x16x32_bf16 v[2:5], v[166:169], v[206:209], v[2:5]
	v_mfma_f32_16x16x32_bf16 v[34:37], v[170:173], v[202:205], v[10:13]
	v_mfma_f32_16x16x32_bf16 v[6:9], v[150:153], v[210:213], v[6:9]
	v_mfma_f32_16x16x32_bf16 v[2:5], v[170:173], v[210:213], v[2:5]
	s_setprio 0
	s_barrier
	s_add_i32 s71, s71, 2
	s_add_u32 s0, s0, 0x100
	s_addc_u32 s1, s1, 0
	s_add_u32 s59, s59, 0x100
	s_addc_u32 s70, s70, 0
	s_cmp_gt_u32 s71, 13
	s_cbranch_scc0 .LBB0_231
	s_and_b64 vcc, exec, s[48:49]
	s_cbranch_vccz .LBB0_234
	s_barrier

.LBB0_560:
	s_add_u32 s6, s40, 0xfffc0080
	s_addc_u32 s7, s41, -1
	s_add_i32 s24, 0, 0x10000
	s_cmp_eq_u32 s66, 12
	s_cselect_b32 s53, s47, s7
	s_cselect_b32 s52, s62, s6
	v_add_u32_e32 v0, s24, v193
	s_cselect_b32 s43, s45, s65
	s_cselect_b32 s42, s63, s64
	s_add_i32 s6, 0, 0x14000
	ds_read_b128 v[74:77], v0
	ds_read_b128 v[86:89], v0 offset:1024
	ds_read_b128 v[98:101], v0 offset:2048
	ds_read_b128 v[102:105], v0 offset:3072
	v_add_u32_e32 v0, s6, v193
	ds_read_b128 v[118:121], v0
	ds_read_b128 v[126:129], v0 offset:1024
	ds_read_b128 v[138:141], v0 offset:2048
	ds_read_b128 v[142:145], v0 offset:3072
	s_add_i32 m0, s55, 0xc000
	ds_read_b128 v[154:157], v213
	ds_read_b128 v[162:165], v213 offset:1024
	ds_read_b128 v[184:187], v213 offset:2048
	ds_read_b128 v[194:197], v213 offset:3072
	ds_read_b128 v[198:201], v213 offset:4096
	ds_read_b128 v[214:217], v213 offset:5120
	ds_read_b128 v[218:221], v213 offset:6144
	ds_read_b128 v[222:225], v213 offset:7168
	global_load_lds_dwordx4 v180, s[40:41]
	s_add_i32 m0, s55, 0xe000
	s_nop 0
	global_load_lds_dwordx4 v182, s[40:41]
	s_waitcnt vmcnt(8)
	s_waitcnt lgkmcnt(0)
	s_barrier
	s_setprio 1
	v_mfma_f32_16x16x32_bf16 v[166:169], v[74:77], v[154:157], v[166:169]
	v_mfma_f32_16x16x32_bf16 v[158:161], v[98:101], v[154:157], v[158:161]
	v_mfma_f32_16x16x32_bf16 v[134:137], v[74:77], v[184:187], v[134:137]
	v_mfma_f32_16x16x32_bf16 v[130:133], v[98:101], v[184:187], v[130:133]
	v_mfma_f32_16x16x32_bf16 v[110:113], v[74:77], v[198:201], v[110:113]
	v_mfma_f32_16x16x32_bf16 v[106:109], v[98:101], v[198:201], v[106:109]
	v_mfma_f32_16x16x32_bf16 v[82:85], v[74:77], v[218:221], v[82:85]
	v_mfma_f32_16x16x32_bf16 v[78:81], v[98:101], v[218:221], v[78:81]
	v_mfma_f32_16x16x32_bf16 v[166:169], v[86:89], v[162:165], v[166:169]
	v_mfma_f32_16x16x32_bf16 v[158:161], v[102:105], v[162:165], v[158:161]
	v_mfma_f32_16x16x32_bf16 v[134:137], v[86:89], v[194:197], v[134:137]
	v_mfma_f32_16x16x32_bf16 v[130:133], v[102:105], v[194:197], v[130:133]
	v_mfma_f32_16x16x32_bf16 v[110:113], v[86:89], v[214:217], v[110:113]
	v_mfma_f32_16x16x32_bf16 v[106:109], v[102:105], v[214:217], v[106:109]
	v_mfma_f32_16x16x32_bf16 v[82:85], v[86:89], v[222:225], v[82:85]
	v_mfma_f32_16x16x32_bf16 v[78:81], v[102:105], v[222:225], v[78:81]
	v_mfma_f32_16x16x32_bf16 v[150:153], v[118:121], v[154:157], v[150:153]
	v_mfma_f32_16x16x32_bf16 v[146:149], v[138:141], v[154:157], v[146:149]
	v_mfma_f32_16x16x32_bf16 v[122:125], v[118:121], v[184:187], v[122:125]
	v_mfma_f32_16x16x32_bf16 v[114:117], v[138:141], v[184:187], v[114:117]
	v_mfma_f32_16x16x32_bf16 v[94:97], v[118:121], v[198:201], v[94:97]
	v_mfma_f32_16x16x32_bf16 v[90:93], v[138:141], v[198:201], v[90:93]
	v_mfma_f32_16x16x32_bf16 v[70:73], v[118:121], v[218:221], v[70:73]
	v_mfma_f32_16x16x32_bf16 v[66:69], v[138:141], v[218:221], v[66:69]
	v_mfma_f32_16x16x32_bf16 v[150:153], v[126:129], v[162:165], v[150:153]
	v_mfma_f32_16x16x32_bf16 v[146:149], v[142:145], v[162:165], v[146:149]
	v_mfma_f32_16x16x32_bf16 v[122:125], v[126:129], v[194:197], v[122:125]
	v_mfma_f32_16x16x32_bf16 v[114:117], v[142:145], v[194:197], v[114:117]
	v_mfma_f32_16x16x32_bf16 v[94:97], v[126:129], v[214:217], v[94:97]
	v_mfma_f32_16x16x32_bf16 v[90:93], v[142:145], v[214:217], v[90:93]
	v_mfma_f32_16x16x32_bf16 v[70:73], v[126:129], v[222:225], v[70:73]
	v_mfma_f32_16x16x32_bf16 v[66:69], v[142:145], v[222:225], v[66:69]
	s_setprio 0
	s_barrier
	s_add_i32 s7, s24, s54
	s_mov_b32 m0, s7
	ds_read_b128 v[154:157], v213 offset:16384
	ds_read_b128 v[162:165], v213 offset:17408
	ds_read_b128 v[184:187], v213 offset:18432
	ds_read_b128 v[194:197], v213 offset:19456
	ds_read_b128 v[198:201], v213 offset:20480
	ds_read_b128 v[214:217], v213 offset:21504
	ds_read_b128 v[218:221], v213 offset:22528
	ds_read_b128 v[222:225], v213 offset:23552
	global_load_lds_dwordx4 v174, s[42:43]
	s_add_i32 m0, s7, 0x2000
	s_add_u32 s24, s42, 0x40000
	s_addc_u32 s25, s43, 0
	s_add_i32 s6, s6, s54
	global_load_lds_dwordx4 v170, s[42:43]
	s_mov_b32 m0, s6
	s_nop 0
	global_load_lds_dwordx4 v174, s[24:25]
	s_add_i32 m0, s6, 0x2000
	s_nop 0
	global_load_lds_dwordx4 v170, s[24:25]
	s_mov_b32 m0, s55
	s_nop 0
	global_load_lds_dwordx4 v176, s[52:53]
	s_mov_b32 m0, s56
	s_nop 0
	global_load_lds_dwordx4 v172, s[52:53]
	s_waitcnt vmcnt(8)
	s_waitcnt lgkmcnt(0)
	s_barrier
	s_setprio 1
	v_mfma_f32_16x16x32_bf16 v[62:65], v[74:77], v[154:157], v[62:65]
	v_mfma_f32_16x16x32_bf16 v[58:61], v[98:101], v[154:157], v[58:61]
	v_mfma_f32_16x16x32_bf16 v[46:49], v[74:77], v[184:187], v[46:49]
	v_mfma_f32_16x16x32_bf16 v[42:45], v[98:101], v[184:187], v[42:45]
	v_mfma_f32_16x16x32_bf16 v[30:33], v[74:77], v[198:201], v[30:33]
	v_mfma_f32_16x16x32_bf16 v[26:29], v[98:101], v[198:201], v[26:29]
	v_mfma_f32_16x16x32_bf16 v[14:17], v[74:77], v[218:221], v[14:17]
	v_mfma_f32_16x16x32_bf16 v[10:13], v[98:101], v[218:221], v[10:13]
	v_mfma_f32_16x16x32_bf16 v[62:65], v[86:89], v[162:165], v[62:65]
	v_mfma_f32_16x16x32_bf16 v[58:61], v[102:105], v[162:165], v[58:61]
	v_mfma_f32_16x16x32_bf16 v[46:49], v[86:89], v[194:197], v[46:49]
	v_mfma_f32_16x16x32_bf16 v[42:45], v[102:105], v[194:197], v[42:45]
	v_mfma_f32_16x16x32_bf16 v[30:33], v[86:89], v[214:217], v[30:33]
	v_mfma_f32_16x16x32_bf16 v[26:29], v[102:105], v[214:217], v[26:29]
	v_mfma_f32_16x16x32_bf16 v[14:17], v[86:89], v[222:225], v[14:17]
	v_mfma_f32_16x16x32_bf16 v[10:13], v[102:105], v[222:225], v[10:13]
	v_mfma_f32_16x16x32_bf16 v[54:57], v[118:121], v[154:157], v[54:57]
	v_mfma_f32_16x16x32_bf16 v[50:53], v[138:141], v[154:157], v[50:53]
	v_mfma_f32_16x16x32_bf16 v[38:41], v[118:121], v[184:187], v[38:41]
	v_mfma_f32_16x16x32_bf16 v[34:37], v[138:141], v[184:187], v[34:37]
	v_mfma_f32_16x16x32_bf16 v[22:25], v[118:121], v[198:201], v[22:25]
	v_mfma_f32_16x16x32_bf16 v[18:21], v[138:141], v[198:201], v[18:21]
	v_mfma_f32_16x16x32_bf16 v[6:9], v[118:121], v[218:221], v[6:9]
	v_mfma_f32_16x16x32_bf16 v[2:5], v[138:141], v[218:221], v[2:5]
	v_mfma_f32_16x16x32_bf16 v[54:57], v[126:129], v[162:165], v[54:57]
	v_mfma_f32_16x16x32_bf16 v[50:53], v[142:145], v[162:165], v[50:53]
	v_mfma_f32_16x16x32_bf16 v[38:41], v[126:129], v[194:197], v[38:41]
	v_mfma_f32_16x16x32_bf16 v[34:37], v[142:145], v[194:197], v[34:37]
	v_mfma_f32_16x16x32_bf16 v[22:25], v[126:129], v[214:217], v[22:25]
	v_mfma_f32_16x16x32_bf16 v[18:21], v[142:145], v[214:217], v[18:21]
	v_mfma_f32_16x16x32_bf16 v[6:9], v[126:129], v[222:225], v[6:9]
	v_mfma_f32_16x16x32_bf16 v[2:5], v[142:145], v[222:225], v[2:5]
	s_setprio 0
	s_barrier
	s_add_i32 s6, 0, 0x18000
	v_add_u32_e32 v0, s6, v193
	s_add_i32 s7, 0, 0x1c000
	ds_read_b128 v[74:77], v0
	ds_read_b128 v[86:89], v0 offset:1024
	ds_read_b128 v[98:101], v0 offset:2048
	ds_read_b128 v[102:105], v0 offset:3072
	v_add_u32_e32 v0, s7, v193
	ds_read_b128 v[118:121], v0
	ds_read_b128 v[126:129], v0 offset:1024
	ds_read_b128 v[138:141], v0 offset:2048
	ds_read_b128 v[142:145], v0 offset:3072
	s_add_u32 s24, s52, 0x40000
	s_addc_u32 s25, s53, 0
	s_mov_b32 m0, s57
	ds_read_b128 v[154:157], v213 offset:32768
	ds_read_b128 v[162:165], v213 offset:33792
	ds_read_b128 v[184:187], v213 offset:34816
	ds_read_b128 v[194:197], v213 offset:35840
	ds_read_b128 v[198:201], v213 offset:36864
	ds_read_b128 v[214:217], v213 offset:37888
	ds_read_b128 v[218:221], v213 offset:38912
	ds_read_b128 v[222:225], v213 offset:39936
	global_load_lds_dwordx4 v176, s[24:25]
	s_mov_b32 m0, s58
	s_nop 0
	global_load_lds_dwordx4 v172, s[24:25]
	s_waitcnt vmcnt(8)
	s_waitcnt lgkmcnt(0)
	s_barrier
	s_setprio 1
	v_mfma_f32_16x16x32_bf16 v[166:169], v[74:77], v[154:157], v[166:169]
	v_mfma_f32_16x16x32_bf16 v[158:161], v[98:101], v[154:157], v[158:161]
	v_mfma_f32_16x16x32_bf16 v[134:137], v[74:77], v[184:187], v[134:137]
	v_mfma_f32_16x16x32_bf16 v[130:133], v[98:101], v[184:187], v[130:133]
	v_mfma_f32_16x16x32_bf16 v[110:113], v[74:77], v[198:201], v[110:113]
	v_mfma_f32_16x16x32_bf16 v[106:109], v[98:101], v[198:201], v[106:109]
	v_mfma_f32_16x16x32_bf16 v[82:85], v[74:77], v[218:221], v[82:85]
	v_mfma_f32_16x16x32_bf16 v[78:81], v[98:101], v[218:221], v[78:81]
	v_mfma_f32_16x16x32_bf16 v[166:169], v[86:89], v[162:165], v[166:169]
	v_mfma_f32_16x16x32_bf16 v[158:161], v[102:105], v[162:165], v[158:161]
	v_mfma_f32_16x16x32_bf16 v[134:137], v[86:89], v[194:197], v[134:137]
	v_mfma_f32_16x16x32_bf16 v[130:133], v[102:105], v[194:197], v[130:133]
	v_mfma_f32_16x16x32_bf16 v[110:113], v[86:89], v[214:217], v[110:113]
	v_mfma_f32_16x16x32_bf16 v[106:109], v[102:105], v[214:217], v[106:109]
	v_mfma_f32_16x16x32_bf16 v[82:85], v[86:89], v[222:225], v[82:85]
	v_mfma_f32_16x16x32_bf16 v[78:81], v[102:105], v[222:225], v[78:81]
	v_mfma_f32_16x16x32_bf16 v[150:153], v[118:121], v[154:157], v[150:153]
	v_mfma_f32_16x16x32_bf16 v[146:149], v[138:141], v[154:157], v[146:149]
	v_mfma_f32_16x16x32_bf16 v[122:125], v[118:121], v[184:187], v[122:125]
	v_mfma_f32_16x16x32_bf16 v[114:117], v[138:141], v[184:187], v[114:117]
	v_mfma_f32_16x16x32_bf16 v[94:97], v[118:121], v[198:201], v[94:97]
	v_mfma_f32_16x16x32_bf16 v[90:93], v[138:141], v[198:201], v[90:93]
	v_mfma_f32_16x16x32_bf16 v[70:73], v[118:121], v[218:221], v[70:73]
	v_mfma_f32_16x16x32_bf16 v[66:69], v[138:141], v[218:221], v[66:69]
	v_mfma_f32_16x16x32_bf16 v[150:153], v[126:129], v[162:165], v[150:153]
	v_mfma_f32_16x16x32_bf16 v[146:149], v[142:145], v[162:165], v[146:149]
	v_mfma_f32_16x16x32_bf16 v[122:125], v[126:129], v[194:197], v[122:125]
	v_mfma_f32_16x16x32_bf16 v[114:117], v[142:145], v[194:197], v[114:117]
	v_mfma_f32_16x16x32_bf16 v[94:97], v[126:129], v[214:217], v[94:97]
	v_mfma_f32_16x16x32_bf16 v[90:93], v[142:145], v[214:217], v[90:93]
	v_mfma_f32_16x16x32_bf16 v[70:73], v[126:129], v[222:225], v[70:73]
	v_mfma_f32_16x16x32_bf16 v[66:69], v[142:145], v[222:225], v[66:69]
	s_setprio 0
	s_barrier
	s_add_i32 s6, s6, s54
	s_add_i32 m0, s6, 0xffffff80
	ds_read_b128 v[154:157], v213 offset:49152
	ds_read_b128 v[162:165], v213 offset:50176
	ds_read_b128 v[184:187], v213 offset:51200
	ds_read_b128 v[194:197], v213 offset:52224
	ds_read_b128 v[198:201], v213 offset:53248
	ds_read_b128 v[214:217], v213 offset:54272
	ds_read_b128 v[218:221], v213 offset:55296
	ds_read_b128 v[222:225], v213 offset:56320
	global_load_lds_dwordx4 v174, s[42:43] offset:128
	s_add_i32 m0, s6, 0x1f80
	s_add_u32 s24, s42, 0x40080
	s_addc_u32 s25, s43, 0
	s_add_i32 s6, s7, s54
	global_load_lds_dwordx4 v170, s[42:43] offset:128
	s_mov_b32 m0, s6
	s_nop 0
	global_load_lds_dwordx4 v174, s[24:25]
	s_add_i32 m0, s6, 0x2000
	s_nop 0
	global_load_lds_dwordx4 v170, s[24:25]
	s_add_i32 m0, s59, 0xffffff80
	s_nop 0
	global_load_lds_dwordx4 v176, s[52:53] offset:128
	s_add_i32 m0, s60, 0xffffff80
	s_nop 0
	global_load_lds_dwordx4 v172, s[52:53] offset:128
	s_waitcnt vmcnt(8)
	s_waitcnt lgkmcnt(0)
	s_barrier
	s_setprio 1
	v_mfma_f32_16x16x32_bf16 v[62:65], v[74:77], v[154:157], v[62:65]
	v_mfma_f32_16x16x32_bf16 v[58:61], v[98:101], v[154:157], v[58:61]
	v_mfma_f32_16x16x32_bf16 v[46:49], v[74:77], v[184:187], v[46:49]
	v_mfma_f32_16x16x32_bf16 v[42:45], v[98:101], v[184:187], v[42:45]
	v_mfma_f32_16x16x32_bf16 v[30:33], v[74:77], v[198:201], v[30:33]
	v_mfma_f32_16x16x32_bf16 v[26:29], v[98:101], v[198:201], v[26:29]
	v_mfma_f32_16x16x32_bf16 v[14:17], v[74:77], v[218:221], v[14:17]
	v_mfma_f32_16x16x32_bf16 v[10:13], v[98:101], v[218:221], v[10:13]
	v_mfma_f32_16x16x32_bf16 v[62:65], v[86:89], v[162:165], v[62:65]
	v_mfma_f32_16x16x32_bf16 v[58:61], v[102:105], v[162:165], v[58:61]
	v_mfma_f32_16x16x32_bf16 v[46:49], v[86:89], v[194:197], v[46:49]
	v_mfma_f32_16x16x32_bf16 v[42:45], v[102:105], v[194:197], v[42:45]
	v_mfma_f32_16x16x32_bf16 v[30:33], v[86:89], v[214:217], v[30:33]
	v_mfma_f32_16x16x32_bf16 v[26:29], v[102:105], v[214:217], v[26:29]
	v_mfma_f32_16x16x32_bf16 v[14:17], v[86:89], v[222:225], v[14:17]
	v_mfma_f32_16x16x32_bf16 v[10:13], v[102:105], v[222:225], v[10:13]
	v_mfma_f32_16x16x32_bf16 v[54:57], v[118:121], v[154:157], v[54:57]
	v_mfma_f32_16x16x32_bf16 v[50:53], v[138:141], v[154:157], v[50:53]
	v_mfma_f32_16x16x32_bf16 v[38:41], v[118:121], v[184:187], v[38:41]
	v_mfma_f32_16x16x32_bf16 v[34:37], v[138:141], v[184:187], v[34:37]
	v_mfma_f32_16x16x32_bf16 v[22:25], v[118:121], v[198:201], v[22:25]
	v_mfma_f32_16x16x32_bf16 v[18:21], v[138:141], v[198:201], v[18:21]
	v_mfma_f32_16x16x32_bf16 v[6:9], v[118:121], v[218:221], v[6:9]
	v_mfma_f32_16x16x32_bf16 v[2:5], v[138:141], v[218:221], v[2:5]
	v_mfma_f32_16x16x32_bf16 v[54:57], v[126:129], v[162:165], v[54:57]
	v_mfma_f32_16x16x32_bf16 v[50:53], v[142:145], v[162:165], v[50:53]
	v_mfma_f32_16x16x32_bf16 v[38:41], v[126:129], v[194:197], v[38:41]
	v_mfma_f32_16x16x32_bf16 v[34:37], v[142:145], v[194:197], v[34:37]
	v_mfma_f32_16x16x32_bf16 v[22:25], v[126:129], v[214:217], v[22:25]
	v_mfma_f32_16x16x32_bf16 v[18:21], v[142:145], v[214:217], v[18:21]
	v_mfma_f32_16x16x32_bf16 v[6:9], v[126:129], v[222:225], v[6:9]
	v_mfma_f32_16x16x32_bf16 v[2:5], v[142:145], v[222:225], v[2:5]
	s_setprio 0
	s_barrier
	s_add_i32 s66, s66, 2
	s_add_u32 s40, s40, 0x100
	s_addc_u32 s41, s41, 0
	s_add_u32 s64, s64, 0x100
	s_addc_u32 s65, s65, 0
	s_cmp_gt_u32 s66, 13
	s_cbranch_scc0 .LBB0_560
	s_and_b64 vcc, exec, s[26:27]
	s_cbranch_vccz .LBB0_563
	s_barrier

.LBB0_763:
	s_add_i32 s25, s24, 2
	s_add_u32 s6, s50, 0x80
	s_addc_u32 s7, s51, 0
	s_add_i32 s55, 0, 0x10000
	s_cmp_eq_u32 s67, s24
	s_cselect_b32 s53, s41, s7
	s_cselect_b32 s52, s40, s6
	s_cselect_b32 s7, s49, s54
	s_cselect_b32 s6, s48, s37
	s_add_i32 s24, 0, 0x14000
	v_add_u32_e32 v142, s55, v188
	v_add_u32_e32 v171, s24, v188
	ds_read_b128 v[122:125], v142
	ds_read_b128 v[134:137], v142 offset:1024
	ds_read_b128 v[138:141], v142 offset:2048
	ds_read_b128 v[142:145], v142 offset:3072
	ds_read_b128 v[146:149], v171
	ds_read_b128 v[150:153], v171 offset:1024
	ds_read_b128 v[154:157], v171 offset:2048
	ds_read_b128 v[172:175], v171 offset:3072
	s_add_i32 m0, s57, 0xc000
	ds_read_b128 v[176:179], v190
	ds_read_b128 v[180:183], v190 offset:1024
	ds_read_b128 v[192:195], v190 offset:2048
	ds_read_b128 v[196:199], v190 offset:3072
	ds_read_b128 v[200:203], v190 offset:4096
	ds_read_b128 v[204:207], v190 offset:5120
	ds_read_b128 v[208:211], v190 offset:6144
	ds_read_b128 v[212:215], v190 offset:7168
	global_load_lds_dwordx4 v166, s[50:51]
	s_add_i32 m0, s57, 0xe000
	s_nop 0
	global_load_lds_dwordx4 v168, s[50:51]
	s_waitcnt vmcnt(8)
	s_waitcnt lgkmcnt(0)
	s_barrier
	s_setprio 1
	v_mfma_f32_16x16x32_bf16 v[130:133], v[122:125], v[176:179], v[130:133]
	v_mfma_f32_16x16x32_bf16 v[126:129], v[138:141], v[176:179], v[126:129]
	v_mfma_f32_16x16x32_bf16 v[110:113], v[122:125], v[192:195], v[110:113]
	v_mfma_f32_16x16x32_bf16 v[106:109], v[138:141], v[192:195], v[106:109]
	v_mfma_f32_16x16x32_bf16 v[94:97], v[122:125], v[200:203], v[94:97]
	v_mfma_f32_16x16x32_bf16 v[90:93], v[138:141], v[200:203], v[90:93]
	v_mfma_f32_16x16x32_bf16 v[78:81], v[122:125], v[208:211], v[78:81]
	v_mfma_f32_16x16x32_bf16 v[74:77], v[138:141], v[208:211], v[74:77]
	v_mfma_f32_16x16x32_bf16 v[130:133], v[134:137], v[180:183], v[130:133]
	v_mfma_f32_16x16x32_bf16 v[126:129], v[142:145], v[180:183], v[126:129]
	v_mfma_f32_16x16x32_bf16 v[110:113], v[134:137], v[196:199], v[110:113]
	v_mfma_f32_16x16x32_bf16 v[106:109], v[142:145], v[196:199], v[106:109]
	v_mfma_f32_16x16x32_bf16 v[94:97], v[134:137], v[204:207], v[94:97]
	v_mfma_f32_16x16x32_bf16 v[90:93], v[142:145], v[204:207], v[90:93]
	v_mfma_f32_16x16x32_bf16 v[78:81], v[134:137], v[212:215], v[78:81]
	v_mfma_f32_16x16x32_bf16 v[74:77], v[142:145], v[212:215], v[74:77]
	v_mfma_f32_16x16x32_bf16 v[118:121], v[146:149], v[176:179], v[118:121]
	v_mfma_f32_16x16x32_bf16 v[114:117], v[154:157], v[176:179], v[114:117]
	v_mfma_f32_16x16x32_bf16 v[102:105], v[146:149], v[192:195], v[102:105]
	v_mfma_f32_16x16x32_bf16 v[98:101], v[154:157], v[192:195], v[98:101]
	v_mfma_f32_16x16x32_bf16 v[86:89], v[146:149], v[200:203], v[86:89]
	v_mfma_f32_16x16x32_bf16 v[82:85], v[154:157], v[200:203], v[82:85]
	v_mfma_f32_16x16x32_bf16 v[70:73], v[146:149], v[208:211], v[70:73]
	v_mfma_f32_16x16x32_bf16 v[66:69], v[154:157], v[208:211], v[66:69]
	v_mfma_f32_16x16x32_bf16 v[118:121], v[150:153], v[180:183], v[118:121]
	v_mfma_f32_16x16x32_bf16 v[114:117], v[172:175], v[180:183], v[114:117]
	v_mfma_f32_16x16x32_bf16 v[102:105], v[150:153], v[196:199], v[102:105]
	v_mfma_f32_16x16x32_bf16 v[98:101], v[172:175], v[196:199], v[98:101]
	v_mfma_f32_16x16x32_bf16 v[86:89], v[150:153], v[204:207], v[86:89]
	v_mfma_f32_16x16x32_bf16 v[82:85], v[172:175], v[204:207], v[82:85]
	v_mfma_f32_16x16x32_bf16 v[70:73], v[150:153], v[212:215], v[70:73]
	v_mfma_f32_16x16x32_bf16 v[66:69], v[172:175], v[212:215], v[66:69]
	s_setprio 0
	s_barrier
	s_add_i32 s55, s55, s56
	s_mov_b64 s[98:99], s[6:7]
	s_mov_b32 m0, s55
	ds_read_b128 v[176:179], v190 offset:16384
	ds_read_b128 v[180:183], v190 offset:17408
	ds_read_b128 v[192:195], v190 offset:18432
	ds_read_b128 v[196:199], v190 offset:19456
	ds_read_b128 v[200:203], v190 offset:20480
	ds_read_b128 v[204:207], v190 offset:21504
	ds_read_b128 v[208:211], v190 offset:22528
	ds_read_b128 v[212:215], v190 offset:23552
	global_load_lds_dwordx4 v162, s[98:99]
	s_add_i32 m0, s55, 0x2000
	s_add_u32 s6, s6, s8
	s_addc_u32 s7, s7, 0
	s_add_i32 s24, s24, s56
	global_load_lds_dwordx4 v158, s[98:99]
	s_mov_b64 s[100:101], s[6:7]
	s_mov_b32 m0, s24
	s_nop 0
	global_load_lds_dwordx4 v162, s[100:101]
	s_add_i32 m0, s24, 0x2000
	s_nop 0
	global_load_lds_dwordx4 v158, s[100:101]
	s_mov_b32 m0, s57
	s_nop 0
	global_load_lds_dwordx4 v164, s[52:53]
	s_mov_b32 m0, s58
	s_nop 0
	global_load_lds_dwordx4 v160, s[52:53]
	s_waitcnt vmcnt(8)
	s_waitcnt lgkmcnt(0)
	s_barrier
	s_setprio 1
	v_mfma_f32_16x16x32_bf16 v[62:65], v[122:125], v[176:179], v[62:65]
	v_mfma_f32_16x16x32_bf16 v[58:61], v[138:141], v[176:179], v[58:61]
	v_mfma_f32_16x16x32_bf16 v[46:49], v[122:125], v[192:195], v[46:49]
	v_mfma_f32_16x16x32_bf16 v[42:45], v[138:141], v[192:195], v[42:45]
	v_mfma_f32_16x16x32_bf16 v[30:33], v[122:125], v[200:203], v[30:33]
	v_mfma_f32_16x16x32_bf16 v[26:29], v[138:141], v[200:203], v[26:29]
	v_mfma_f32_16x16x32_bf16 v[14:17], v[122:125], v[208:211], v[14:17]
	v_mfma_f32_16x16x32_bf16 v[10:13], v[138:141], v[208:211], v[10:13]
	v_mfma_f32_16x16x32_bf16 v[62:65], v[134:137], v[180:183], v[62:65]
	v_mfma_f32_16x16x32_bf16 v[58:61], v[142:145], v[180:183], v[58:61]
	v_mfma_f32_16x16x32_bf16 v[46:49], v[134:137], v[196:199], v[46:49]
	v_mfma_f32_16x16x32_bf16 v[42:45], v[142:145], v[196:199], v[42:45]
	v_mfma_f32_16x16x32_bf16 v[30:33], v[134:137], v[204:207], v[30:33]
	v_mfma_f32_16x16x32_bf16 v[26:29], v[142:145], v[204:207], v[26:29]
	v_mfma_f32_16x16x32_bf16 v[14:17], v[134:137], v[212:215], v[14:17]
	v_mfma_f32_16x16x32_bf16 v[10:13], v[142:145], v[212:215], v[10:13]
	v_mfma_f32_16x16x32_bf16 v[54:57], v[146:149], v[176:179], v[54:57]
	v_mfma_f32_16x16x32_bf16 v[50:53], v[154:157], v[176:179], v[50:53]
	v_mfma_f32_16x16x32_bf16 v[38:41], v[146:149], v[192:195], v[38:41]
	v_mfma_f32_16x16x32_bf16 v[34:37], v[154:157], v[192:195], v[34:37]
	v_mfma_f32_16x16x32_bf16 v[22:25], v[146:149], v[200:203], v[22:25]
	v_mfma_f32_16x16x32_bf16 v[18:21], v[154:157], v[200:203], v[18:21]
	v_mfma_f32_16x16x32_bf16 v[6:9], v[146:149], v[208:211], v[6:9]
	v_mfma_f32_16x16x32_bf16 v[2:5], v[154:157], v[208:211], v[2:5]
	v_mfma_f32_16x16x32_bf16 v[54:57], v[150:153], v[180:183], v[54:57]
	v_mfma_f32_16x16x32_bf16 v[50:53], v[172:175], v[180:183], v[50:53]
	v_mfma_f32_16x16x32_bf16 v[38:41], v[150:153], v[196:199], v[38:41]
	v_mfma_f32_16x16x32_bf16 v[34:37], v[172:175], v[196:199], v[34:37]
	v_mfma_f32_16x16x32_bf16 v[22:25], v[150:153], v[204:207], v[22:25]
	v_mfma_f32_16x16x32_bf16 v[18:21], v[172:175], v[204:207], v[18:21]
	v_mfma_f32_16x16x32_bf16 v[6:9], v[150:153], v[212:215], v[6:9]
	v_mfma_f32_16x16x32_bf16 v[2:5], v[172:175], v[212:215], v[2:5]
	s_setprio 0
	s_barrier
	s_add_i32 s24, 0, 0x18000
	s_add_i32 s55, 0, 0x1c000
	v_add_u32_e32 v142, s24, v188
	v_add_u32_e32 v171, s55, v188
	ds_read_b128 v[122:125], v142
	ds_read_b128 v[134:137], v142 offset:1024
	ds_read_b128 v[138:141], v142 offset:2048
	ds_read_b128 v[142:145], v142 offset:3072
	ds_read_b128 v[146:149], v171
	ds_read_b128 v[150:153], v171 offset:1024
	ds_read_b128 v[154:157], v171 offset:2048
	ds_read_b128 v[172:175], v171 offset:3072
	s_add_u32 s6, s52, s8
	s_addc_u32 s7, s53, 0
	s_mov_b32 m0, s59
	ds_read_b128 v[176:179], v190 offset:32768
	ds_read_b128 v[180:183], v190 offset:33792
	ds_read_b128 v[192:195], v190 offset:34816
	ds_read_b128 v[196:199], v190 offset:35840
	ds_read_b128 v[200:203], v190 offset:36864
	ds_read_b128 v[204:207], v190 offset:37888
	ds_read_b128 v[208:211], v190 offset:38912
	ds_read_b128 v[212:215], v190 offset:39936
	global_load_lds_dwordx4 v164, s[6:7]
	s_mov_b32 m0, s60
	s_nop 0
	global_load_lds_dwordx4 v160, s[6:7]
	s_waitcnt vmcnt(8)
	s_waitcnt lgkmcnt(0)
	s_barrier
	s_setprio 1
	v_mfma_f32_16x16x32_bf16 v[130:133], v[122:125], v[176:179], v[130:133]
	v_mfma_f32_16x16x32_bf16 v[126:129], v[138:141], v[176:179], v[126:129]
	v_mfma_f32_16x16x32_bf16 v[110:113], v[122:125], v[192:195], v[110:113]
	v_mfma_f32_16x16x32_bf16 v[106:109], v[138:141], v[192:195], v[106:109]
	v_mfma_f32_16x16x32_bf16 v[94:97], v[122:125], v[200:203], v[94:97]
	v_mfma_f32_16x16x32_bf16 v[90:93], v[138:141], v[200:203], v[90:93]
	v_mfma_f32_16x16x32_bf16 v[78:81], v[122:125], v[208:211], v[78:81]
	v_mfma_f32_16x16x32_bf16 v[74:77], v[138:141], v[208:211], v[74:77]
	v_mfma_f32_16x16x32_bf16 v[130:133], v[134:137], v[180:183], v[130:133]
	v_mfma_f32_16x16x32_bf16 v[126:129], v[142:145], v[180:183], v[126:129]
	v_mfma_f32_16x16x32_bf16 v[110:113], v[134:137], v[196:199], v[110:113]
	v_mfma_f32_16x16x32_bf16 v[106:109], v[142:145], v[196:199], v[106:109]
	v_mfma_f32_16x16x32_bf16 v[94:97], v[134:137], v[204:207], v[94:97]
	v_mfma_f32_16x16x32_bf16 v[90:93], v[142:145], v[204:207], v[90:93]
	v_mfma_f32_16x16x32_bf16 v[78:81], v[134:137], v[212:215], v[78:81]
	v_mfma_f32_16x16x32_bf16 v[74:77], v[142:145], v[212:215], v[74:77]
	v_mfma_f32_16x16x32_bf16 v[118:121], v[146:149], v[176:179], v[118:121]
	v_mfma_f32_16x16x32_bf16 v[114:117], v[154:157], v[176:179], v[114:117]
	v_mfma_f32_16x16x32_bf16 v[102:105], v[146:149], v[192:195], v[102:105]
	v_mfma_f32_16x16x32_bf16 v[98:101], v[154:157], v[192:195], v[98:101]
	v_mfma_f32_16x16x32_bf16 v[86:89], v[146:149], v[200:203], v[86:89]
	v_mfma_f32_16x16x32_bf16 v[82:85], v[154:157], v[200:203], v[82:85]
	v_mfma_f32_16x16x32_bf16 v[70:73], v[146:149], v[208:211], v[70:73]
	v_mfma_f32_16x16x32_bf16 v[66:69], v[154:157], v[208:211], v[66:69]
	v_mfma_f32_16x16x32_bf16 v[118:121], v[150:153], v[180:183], v[118:121]
	v_mfma_f32_16x16x32_bf16 v[114:117], v[172:175], v[180:183], v[114:117]
	v_mfma_f32_16x16x32_bf16 v[102:105], v[150:153], v[196:199], v[102:105]
	v_mfma_f32_16x16x32_bf16 v[98:101], v[172:175], v[196:199], v[98:101]
	v_mfma_f32_16x16x32_bf16 v[86:89], v[150:153], v[204:207], v[86:89]
	v_mfma_f32_16x16x32_bf16 v[82:85], v[172:175], v[204:207], v[82:85]
	v_mfma_f32_16x16x32_bf16 v[70:73], v[150:153], v[212:215], v[70:73]
	v_mfma_f32_16x16x32_bf16 v[66:69], v[172:175], v[212:215], v[66:69]
	s_setprio 0
	s_barrier
	s_add_i32 s6, s24, s56
	s_add_i32 m0, s6, 0xffffff80
	ds_read_b128 v[176:179], v190 offset:49152
	ds_read_b128 v[180:183], v190 offset:50176
	ds_read_b128 v[192:195], v190 offset:51200
	ds_read_b128 v[196:199], v190 offset:52224
	ds_read_b128 v[200:203], v190 offset:53248
	ds_read_b128 v[204:207], v190 offset:54272
	ds_read_b128 v[208:211], v190 offset:55296
	ds_read_b128 v[212:215], v190 offset:56320
	global_load_lds_dwordx4 v162, s[98:99] offset:128
	s_add_i32 m0, s6, 0x1f80
	s_add_i32 s6, s55, s56
	global_load_lds_dwordx4 v158, s[98:99] offset:128
	s_add_i32 m0, s6, 0xffffff80
	s_nop 0
	global_load_lds_dwordx4 v162, s[100:101] offset:128
	s_add_i32 m0, s6, 0x1f80
	s_nop 0
	global_load_lds_dwordx4 v158, s[100:101] offset:128
	s_add_i32 m0, s65, 0xffffff80
	s_nop 0
	global_load_lds_dwordx4 v164, s[52:53] offset:128
	s_add_i32 m0, s66, 0xffffff80
	s_nop 0
	global_load_lds_dwordx4 v160, s[52:53] offset:128
	s_waitcnt vmcnt(8)
	s_waitcnt lgkmcnt(0)
	s_barrier
	s_setprio 1
	v_mfma_f32_16x16x32_bf16 v[62:65], v[122:125], v[176:179], v[62:65]
	v_mfma_f32_16x16x32_bf16 v[58:61], v[138:141], v[176:179], v[58:61]
	v_mfma_f32_16x16x32_bf16 v[46:49], v[122:125], v[192:195], v[46:49]
	v_mfma_f32_16x16x32_bf16 v[42:45], v[138:141], v[192:195], v[42:45]
	v_mfma_f32_16x16x32_bf16 v[30:33], v[122:125], v[200:203], v[30:33]
	v_mfma_f32_16x16x32_bf16 v[26:29], v[138:141], v[200:203], v[26:29]
	v_mfma_f32_16x16x32_bf16 v[14:17], v[122:125], v[208:211], v[14:17]
	v_mfma_f32_16x16x32_bf16 v[10:13], v[138:141], v[208:211], v[10:13]
	v_mfma_f32_16x16x32_bf16 v[62:65], v[134:137], v[180:183], v[62:65]
	v_mfma_f32_16x16x32_bf16 v[58:61], v[142:145], v[180:183], v[58:61]
	v_mfma_f32_16x16x32_bf16 v[46:49], v[134:137], v[196:199], v[46:49]
	v_mfma_f32_16x16x32_bf16 v[42:45], v[142:145], v[196:199], v[42:45]
	v_mfma_f32_16x16x32_bf16 v[30:33], v[134:137], v[204:207], v[30:33]
	v_mfma_f32_16x16x32_bf16 v[26:29], v[142:145], v[204:207], v[26:29]
	v_mfma_f32_16x16x32_bf16 v[14:17], v[134:137], v[212:215], v[14:17]
	v_mfma_f32_16x16x32_bf16 v[10:13], v[142:145], v[212:215], v[10:13]
	v_mfma_f32_16x16x32_bf16 v[54:57], v[146:149], v[176:179], v[54:57]
	v_mfma_f32_16x16x32_bf16 v[50:53], v[154:157], v[176:179], v[50:53]
	v_mfma_f32_16x16x32_bf16 v[38:41], v[146:149], v[192:195], v[38:41]
	v_mfma_f32_16x16x32_bf16 v[34:37], v[154:157], v[192:195], v[34:37]
	v_mfma_f32_16x16x32_bf16 v[22:25], v[146:149], v[200:203], v[22:25]
	v_mfma_f32_16x16x32_bf16 v[18:21], v[154:157], v[200:203], v[18:21]
	v_mfma_f32_16x16x32_bf16 v[6:9], v[146:149], v[208:211], v[6:9]
	v_mfma_f32_16x16x32_bf16 v[2:5], v[154:157], v[208:211], v[2:5]
	v_mfma_f32_16x16x32_bf16 v[54:57], v[150:153], v[180:183], v[54:57]
	v_mfma_f32_16x16x32_bf16 v[50:53], v[172:175], v[180:183], v[50:53]
	v_mfma_f32_16x16x32_bf16 v[38:41], v[150:153], v[196:199], v[38:41]
	v_mfma_f32_16x16x32_bf16 v[34:37], v[172:175], v[196:199], v[34:37]
	v_mfma_f32_16x16x32_bf16 v[22:25], v[150:153], v[204:207], v[22:25]
	v_mfma_f32_16x16x32_bf16 v[18:21], v[172:175], v[204:207], v[18:21]
	v_mfma_f32_16x16x32_bf16 v[6:9], v[150:153], v[212:215], v[6:9]
	v_mfma_f32_16x16x32_bf16 v[2:5], v[172:175], v[212:215], v[2:5]
	s_setprio 0
	s_barrier
	s_add_u32 s50, s50, 0x100
	s_addc_u32 s51, s51, 0
	s_add_u32 s37, s37, 0x100
	s_addc_u32 s54, s54, 0
	s_cmp_ge_u32 s25, s62
	s_mov_b32 s24, s25
	s_cbranch_scc0 .LBB0_763
	s_and_b64 vcc, exec, s[44:45]
	s_cbranch_vccz .LBB0_766
	s_barrier
